# v15 plus four more store-ack-only drains removed in the gated-delta phase (pass-loop top, step C preamble, two early solve rows)
# baseline (speedup 1.0000x reference)
; #define INP(i) (*(const float* const __attribute__((address_space(4)))*)(ka_base() + 8 * (i)))
; __device__ __forceinline__ unsigned cvt_pk_bf16(float lo, float hi) { const f32x2 v = {lo, hi}; const bf16v2_t b = __builtin_convertvector(v, bf16v2_t); return __builtin_bit_cast(unsigned, b); }
; __device__ __forceinline__ void d1_unit(const Params& p, int g, int l, int unit0, int nd1, unsigned char* lds0, const int tidx) {
;     ...
;               const int rr = c - 3 + j;
;               raw[X][j][0] = (u32x4){0u, 0u, 0u, 0u}; raw[X][j][1] = raw[X][j][0];
;               if (c < nvalid) {
;                   if (rr >= 0) { const bf16_t* src = buf + (size_t)(row0 + rr) * 1024 + 128 * h + d0; raw[X][j][0] = *(const u32x4*)src; raw[X][j][1] = *(const u32x4*)(src + 8); }
;                   else if (smp) {
;                       const float* src = INP(2) + (((size_t)l * 8 + sb) * 3 + (rr + 3)) * 3072 + chx;
;                       const f32x4 f0 = *(const f32x4*)src, f1 = *(const f32x4*)(src + 4), f2 = *(const f32x4*)(src + 8), f3 = *(const f32x4*)(src + 12);
;                       raw[X][j][0] = (u32x4){cvt_pk_bf16(f0[0], f0[1]), cvt_pk_bf16(f0[2], f0[3]), cvt_pk_bf16(f1[0], f1[1]), cvt_pk_bf16(f1[2], f1[3])};
;                       raw[X][j][1] = (u32x4){cvt_pk_bf16(f2[0], f2[1]), cvt_pk_bf16(f2[2], f2[3]), cvt_pk_bf16(f3[0], f3[1]), cvt_pk_bf16(f3[2], f3[3])};
.LBB0_234:
	v_or_b32_e32 v192, s2, v133
	v_add_u32_e32 v49, -3, v192
	v_cmp_gt_u32_e64 s[50:51], s24, v192
	v_mov_b32_e32 v4, 0
	v_mov_b32_e32 v8, 0
	v_mov_b32_e32 v9, 0
	v_mov_b32_e32 v10, 0
	v_mov_b32_e32 v11, 0
	v_mov_b32_e32 v0, 0
	v_mov_b32_e32 v1, 0
	v_mov_b32_e32 v2, 0
	v_mov_b32_e32 v3, 0
	s_and_saveexec_b64 s[2:3], s[50:51]
	s_cbranch_execz .LBB0_244
	v_cmp_gt_u32_e32 vcc, 3, v192
	s_and_saveexec_b64 s[14:15], vcc
	s_xor_b64 s[14:15], exec, s[14:15]
	s_cbranch_execz .LBB0_241
	s_andn2_b64 vcc, exec, s[52:53]
	s_mov_b64 s[16:17], -1
	s_cbranch_vccnz .LBB0_238
	s_mov_b64 s[16:17], s[76:77]
	s_load_dwordx2 s[16:17], s[16:17], 0x10
	v_lshl_add_u64 v[0:1], s[64:65], 0, v[192:193]
	s_movk_i32 s22, 0x3000
	v_lshlrev_b32_e32 v2, 2, v140
	v_mov_b32_e32 v3, v193
	s_waitcnt lgkmcnt(0)
	v_mov_b64_e32 v[6:7], s[16:17]
	v_mad_u64_u32 v[6:7], s[16:17], v0, s22, v[6:7]
	v_mov_b32_e32 v0, v7
	v_mad_u64_u32 v[0:1], s[16:17], v1, s22, v[0:1]
	v_mov_b32_e32 v7, v0
	v_lshl_add_u64 v[14:15], v[6:7], 0, v[2:3]
	global_load_dwordx4 v[0:3], v[14:15], off
	global_load_dwordx4 v[6:9], v[14:15], off offset:16
	global_load_dwordx4 v[10:13], v[14:15], off offset:32
	s_nop 0
	global_load_dwordx4 v[14:17], v[14:15], off offset:48
	s_mov_b64 s[16:17], 0
	s_waitcnt vmcnt(3)
	v_cvt_pk_bf16_f32 v0, v0, v1
	v_cvt_pk_bf16_f32 v1, v2, v3
	s_waitcnt vmcnt(2)
	v_cvt_pk_bf16_f32 v2, v6, v7
	v_cvt_pk_bf16_f32 v3, v8, v9
	s_waitcnt vmcnt(1)
	v_cvt_pk_bf16_f32 v8, v10, v11
	v_cvt_pk_bf16_f32 v9, v12, v13
	s_waitcnt vmcnt(0)
	v_cvt_pk_bf16_f32 v10, v14, v15
	v_cvt_pk_bf16_f32 v11, v16, v17

; __device__ __forceinline__ f32x4 mma(bf16x8 x, bf16x8 y, f32x4 c) { return __builtin_amdgcn_mfma_f32_16x16x32_bf16(x, y, c, 0, 0, 0); }
; __device__ __forceinline__ void d1_unit(const Params& p, int g, int l, int unit0, int nd1, unsigned char* lds0, const int tidx) {
;     ...
;     if (active) for (int jb = wid * 8; jb < wid * 8 + 8; ++jb) {
;         const int mat = jb >> 4, ti = (jb >> 2) & 3, tj = jb & 3;
;         f32x4 acc = (f32x4){0.f, 0.f, 0.f, 0.f};
;         if (tj <= ti) {
;             const bf16_t* Y = mat == 0 ? sk : sq;
; #pragma unroll
;             for (int kk = 0; kk < 4; ++kk) {
;                 const bf16x8 xf = *(const bf16x8*)(sk + (16 * tj + fr) * 136 + 32 * kk + 8 * fq);
;                 const bf16x8 yf = *(const bf16x8*)(Y + (16 * ti + fr) * 136 + 32 * kk + 8 * fq);
;                 acc = mma(xf, yf, acc);
;             }
;         }
;         const int i = 16 * ti + fr, j0 = 16 * tj + 4 * fq;
;         const float gi = sGam[i], bi = sBeta[i];
;         float zf = 0.f; asm volatile("" : "+v"(zf));
;         float o[4];
; #pragma unroll
;         for (int jj = 0; jj < 4; ++jj) {
;             const int j = j0 + jj;
;             const bool keep = mat == 0 ? (j < i) : (j <= i);
;             o[jj] = keep ? acc[jj] * __expf(gi - sGam[j]) * (mat == 0 ? bi : 1.0f) : zf;
;         }
;         if (mat == 0) *(f32x4*)(Am + i * 64 + j0) = (f32x4){o[0], o[1], o[2], o[3]};
.LBB0_347:
	v_cndmask_b32_e64 v0, 0, 1, s[4:5]
	s_add_i32 s22, s20, 0x4400
	v_cmp_ne_u32_e64 s[2:3], 1, v0
	s_andn2_b64 vcc, exec, s[4:5]
	s_waitcnt lgkmcnt(0)
	s_barrier
	s_cbranch_vccnz .LBB0_428
	s_lshr_b32 s0, s30, 6
	s_lshl_b32 s0, s0, 5
	v_and_or_b32 v13, s0, 32, v131
	v_lshlrev_b32_e32 v1, 2, v13
	v_add_u32_e32 v2, s31, v1
	ds_read_b32 v2, v2
	s_cmp_gt_u32 s33, 1
	v_add_u32_e32 v0, s20, v196
	s_cselect_b64 s[10:11], -1, 0
	s_cmp_lt_u32 s33, 2
	v_add_u32_e32 v1, s25, v1
	s_cselect_b64 s[4:5], -1, 0
	v_add_u32_e32 v11, v0, v141
	ds_read_b32 v9, v1
	s_waitcnt lgkmcnt(1)
	v_cndmask_b32_e64 v8, 1.0, v2, s[4:5]
	ds_read_b128 v[0:3], v11 offset:17408
	s_and_b64 s[0:1], s[4:5], exec
	s_cselect_b32 s23, s22, s20
	v_mul_u32_u24_e32 v4, 0x110, v13
	v_add3_u32 v10, s23, v4, v196
	ds_read_b128 v[4:7], v11 offset:17472
	ds_read_b128 v[14:17], v10
	ds_read_b128 v[18:21], v10 offset:64
	s_waitcnt lgkmcnt(1)
	v_mfma_f32_16x16x32_bf16 v[0:3], v[0:3], v[14:17], 0
	ds_read_b128 v[14:17], v11 offset:17536
	v_cmp_lt_u32_e32 vcc, v132, v13
	v_lshl_add_u32 v12, v132, 2, s25
	s_waitcnt lgkmcnt(1)
	v_mfma_f32_16x16x32_bf16 v[0:3], v[4:7], v[18:21], v[0:3]
	ds_read_b128 v[4:7], v11 offset:17600
	ds_read_b128 v[18:21], v10 offset:128
	ds_read_b128 v[22:25], v10 offset:192
	s_waitcnt lgkmcnt(1)
	v_mfma_f32_16x16x32_bf16 v[0:3], v[14:17], v[18:21], v[0:3]
	s_waitcnt lgkmcnt(0)
	v_mfma_f32_16x16x32_bf16 v[4:7], v[4:7], v[22:25], v[0:3]
	s_nop 5
	v_cndmask_b32_e64 v0, 0, 1, vcc
	v_cmp_le_u32_e32 vcc, v132, v13
	v_mov_b32_e32 v3, v193
	s_nop 0
	v_cndmask_b32_e64 v1, 0, 1, vcc
	v_cndmask_b32_e64 v0, v1, v0, s[4:5]
	v_and_b32_e32 v0, 1, v0
	v_cmp_eq_u32_e64 s[8:9], 1, v0
	v_mov_b32_e32 v0, v3
	s_and_saveexec_b64 s[0:1], s[8:9]
	s_cbranch_execz .LBB0_350
	ds_read_b32 v0, v12
	s_waitcnt lgkmcnt(0)
	v_sub_f32_e32 v0, v9, v0
	v_mul_f32_e32 v0, 0x3fb8aa3b, v0
	v_exp_f32_e32 v0, v0
	s_nop 0
	v_mul_f32_e32 v0, v4, v0
	v_mul_f32_e32 v0, v8, v0

; __device__ __forceinline__ bf16_t f2bf(float f) { return (bf16_t)(cvt_pk_bf16(f, 0.f) & 0xffffu); }
; __device__ __forceinline__ float bf2f(bf16_t b) { return __uint_as_float(((unsigned)b) << 16); }
; template <int I>
; __device__ __forceinline__ void solve_rows(float (&x)[64], const f32x4* A4, const bf16_t* src, const float* sBeta, const float* sGam, int part, bf16_t* dst, int nvalid) {
;     ...
;         for (int q = 0; q < (I + 3) / 4; ++q) a4[q] = A4[I * 16 + q];
;         float a = bf2f(src[I * 136]) * sBeta[I];
;         if (part == 1) a *= __expf(sGam[I]);
; #pragma unroll
;         for (int j = 0; j < I; ++j) a -= a4[j >> 2][j & 3] * x[j];
;         x[I] = a;
;         if (I < nvalid) *dst = f2bf(a);
.LBB0_439:
	v_pk_mul_f32 v[0:1], v[64:65], v[0:1]
	v_mov_b32_e32 v68, v67
	v_sub_f32_e32 v0, v6, v0
	v_sub_f32_e32 v6, v0, v1
	v_pk_mul_f32 v[0:1], v[68:69], v[2:3]
	v_lshl_add_u64 v[8:9], v[4:5], 0, s[0:1]
	v_sub_f32_e32 v0, v6, v0
	v_sub_f32_e32 v71, v0, v1
	v_cvt_pk_bf16_f32 v0, v71, s0
	global_store_short v[4:5], v0, off
	ds_read_b128 v[0:3], v54 offset:53504
	ds_read_b128 v[4:7], v54 offset:53520
	s_waitcnt lgkmcnt(0)
	ds_read_u16 v5, v108 offset:1360
	ds_read_b32 v6, v107 offset:20
	s_and_b64 vcc, exec, s[50:51]
	s_waitcnt lgkmcnt(0)
	v_lshlrev_b32_e32 v5, 16, v5
	v_mul_f32_e32 v5, v6, v5
	s_cbranch_vccnz .LBB0_441
	ds_read_b32 v6, v106 offset:20
	s_waitcnt lgkmcnt(0)
	v_mul_f32_e32 v6, 0x3fb8aa3b, v6
	v_exp_f32_e32 v6, v6
	s_nop 0
	v_mul_f32_e32 v5, v5, v6
.LBB0_441:
	v_fma_f32 v5, -v64, v0, v5
	v_mov_b32_e32 v0, v1
	v_mov_b32_e32 v1, v2
	v_pk_mul_f32 v[0:1], v[66:67], v[0:1]
	v_mov_b32_e32 v70, v69
	v_sub_f32_e32 v0, v5, v0
	v_sub_f32_e32 v2, v0, v1
	v_pk_mov_b32 v[0:1], v[2:3], v[4:5] op_sel:[1,0]
	v_lshl_add_u64 v[4:5], v[8:9], 0, s[0:1]
	v_pk_mul_f32 v[0:1], v[70:71], v[0:1]
	s_and_b64 vcc, exec, s[50:51]
	v_sub_f32_e32 v0, v2, v0
	v_sub_f32_e32 v73, v0, v1
	v_cvt_pk_bf16_f32 v0, v73, s0
	global_store_short v[8:9], v0, off
	ds_read_u16 v8, v108 offset:1632
	ds_read_b128 v[0:3], v54 offset:53760
	ds_read_b32 v9, v107 offset:24
	ds_read_b64 v[6:7], v54 offset:53776
	s_waitcnt lgkmcnt(0)
	v_lshlrev_b32_e32 v8, 16, v8
	v_mul_f32_e32 v8, v9, v8
	s_cbranch_vccnz .LBB0_443
	ds_read_b32 v9, v106 offset:24
	s_waitcnt lgkmcnt(0)
	v_mul_f32_e32 v9, 0x3fb8aa3b, v9
	v_exp_f32_e32 v9, v9
	s_nop 0
	v_mul_f32_e32 v8, v8, v9
